# v30 stack plus default cache policy for the in-proj output tiles 24..43 (nt elsewhere)
# baseline (speedup 1.0000x reference)
; #define PG8_STAGE(bufoff, gbase, voff) do { _Pragma("unroll") for (int _i = 0; _i < 2; ++_i) \
;         __builtin_amdgcn_global_load_lds((const unsigned*)((const char*)(gbase) + (voff)[_i]), (LAS unsigned*)(lds + (bufoff) + ldsw + _i * 8192), 16, 0, 0); } while (0)
; #define PG8_LDA(dst, b, h) do { _Pragma("unroll") for (int m = 0; m < 4; ++m) _Pragma("unroll") for (int k = 0; k < 2; ++k) dst[m][k] = *(const LAS h8*)(lds + PG8_SA(b, h) + aoff + m * 2048 + k * 1024); } while (0)
; #define PG8_LDB(dst, b, h) do { _Pragma("unroll") for (int n = 0; n < 2; ++n) _Pragma("unroll") for (int k = 0; k < 2; ++k) dst[n][k] = *(const LAS h8*)(lds + PG8_SB(b, h) + boff + n * 2048 + k * 1024); } while (0)
; #define PG8_WAIT_L(n) asm volatile("s_waitcnt lgkmcnt(" #n ")" ::: "memory")
; #define PG8_BAR __builtin_amdgcn_s_barrier()
; #define PG8_SCHED __builtin_amdgcn_sched_barrier(0)
; template <class Epi>
; __device__ __forceinline__ void gemm_phase(LAS unsigned char* lds, const Gemm g, const StaticOrder& S, const Epi& E, const int tid) {
;     ...
;             PG8_LDB(B0, 0, 0); PG8_SCHED; PG8_LDA(At, 0, 0); PG8_STAGE(PG8_SA(1, 1), a1 + hstep, voffA);
;             PG8_WAIT_L(8); PG8_BAR; PG8_WAIT_L(0); PG8_MMA(0, 0, At, B0); PG8_BAR; PG8_SCHED;
;             PG8_LDB(B1, 0, 1); PG8_STAGE(PG8_SB(0, 0), b2, voffB);
;             PG8_BAR; PG8_WAIT_L(0); PG8_MMA(0, 1, At, B1); PG8_BAR;
;             PG8_LDA(At, 0, 1); PG8_STAGE(PG8_SA(0, 0), a2, voffA);
;             PG8_BAR; PG8_WAIT_L(0); PG8_MMA(1, 0, At, B0); PG8_BAR; PG8_SCHED;
.LBB0_332:
	s_add_u32 s18, s14, 0xfff80080
	s_addc_u32 s19, s15, -1
	s_add_i32 s55, 0, 0x10000
	v_add_u32_e32 v157, s55, v140
	s_cmp_eq_u32 s54, 28
	s_cselect_b32 s23, s9, s19
	s_cselect_b32 s22, s50, s18
	s_cselect_b32 s19, s1, s53
	s_cselect_b32 s18, s51, s52
	s_add_i32 m0, s39, 0xc000
	s_nop 0
	global_load_lds_dwordx4 v136, s[14:15]
	s_add_i32 m0, s39, 0xe000
	s_nop 0
	global_load_lds_dwordx4 v138, s[14:15]
	ds_read_b128 v[144:147], v157
	ds_read_b128 v[162:165], v157 offset:1024
	ds_read_b128 v[166:169], v157 offset:2048
	ds_read_b128 v[170:173], v157 offset:3072
	ds_read_b128 v[174:177], v143
	ds_read_b128 v[190:193], v143 offset:1024
	ds_read_b128 v[194:197], v143 offset:2048
	ds_read_b128 v[198:201], v143 offset:3072
	ds_read_b128 v[202:205], v143 offset:4096
	ds_read_b128 v[206:209], v143 offset:5120
	ds_read_b128 v[210:213], v143 offset:6144
	ds_read_b128 v[214:217], v143 offset:7168
	s_waitcnt lgkmcnt(8)
	s_barrier
	s_waitcnt lgkmcnt(7)
	v_mfma_f32_16x16x32_bf16 v[124:127], v[144:147], v[174:177], v[124:127]
	v_mfma_f32_16x16x32_bf16 v[128:131], v[166:169], v[174:177], v[128:131]
	s_waitcnt lgkmcnt(5)
	v_mfma_f32_16x16x32_bf16 v[108:111], v[144:147], v[194:197], v[108:111]
	v_mfma_f32_16x16x32_bf16 v[112:115], v[166:169], v[194:197], v[112:115]
	s_waitcnt lgkmcnt(3)
	v_mfma_f32_16x16x32_bf16 v[92:95], v[144:147], v[202:205], v[92:95]
	v_mfma_f32_16x16x32_bf16 v[96:99], v[166:169], v[202:205], v[96:99]
	s_waitcnt lgkmcnt(1)
	v_mfma_f32_16x16x32_bf16 v[76:79], v[144:147], v[210:213], v[76:79]
	v_mfma_f32_16x16x32_bf16 v[80:83], v[166:169], v[210:213], v[80:83]
	v_mfma_f32_16x16x32_bf16 v[124:127], v[162:165], v[190:193], v[124:127]
	v_mfma_f32_16x16x32_bf16 v[128:131], v[170:173], v[190:193], v[128:131]
	v_mfma_f32_16x16x32_bf16 v[108:111], v[162:165], v[198:201], v[108:111]
	v_mfma_f32_16x16x32_bf16 v[112:115], v[170:173], v[198:201], v[112:115]
	v_mfma_f32_16x16x32_bf16 v[92:95], v[162:165], v[206:209], v[92:95]
	v_mfma_f32_16x16x32_bf16 v[96:99], v[170:173], v[206:209], v[96:99]
	s_waitcnt lgkmcnt(0)
	v_mfma_f32_16x16x32_bf16 v[76:79], v[162:165], v[214:217], v[76:79]
	v_mfma_f32_16x16x32_bf16 v[80:83], v[170:173], v[214:217], v[80:83]
	s_barrier
	s_add_i32 s58, 0, 0x14000
	s_add_i32 s55, s55, s38
	v_add_u32_e32 v157, s58, v140
	v_lshl_add_u64 v[178:179], s[18:19], 0, v[2:3]
	s_mov_b32 m0, s55
	s_nop 0
	global_load_lds_dwordx4 v[178:179], off
	v_lshl_add_u64 v[234:235], s[18:19], 0, v[0:1]
	s_add_i32 m0, s55, 0x2000
	s_nop 0
	global_load_lds_dwordx4 v[234:235], off
	ds_read_b128 v[218:221], v157
	ds_read_b128 v[222:225], v157 offset:1024
	ds_read_b128 v[226:229], v157 offset:2048
	ds_read_b128 v[230:233], v157 offset:3072
	s_barrier
	s_waitcnt lgkmcnt(3)
	v_mfma_f32_16x16x32_bf16 v[116:119], v[218:221], v[174:177], v[116:119]
	s_waitcnt lgkmcnt(1)
	v_mfma_f32_16x16x32_bf16 v[120:123], v[226:229], v[174:177], v[120:123]
	v_mfma_f32_16x16x32_bf16 v[100:103], v[218:221], v[194:197], v[100:103]
	v_mfma_f32_16x16x32_bf16 v[104:107], v[226:229], v[194:197], v[104:107]
	v_mfma_f32_16x16x32_bf16 v[84:87], v[218:221], v[202:205], v[84:87]
	v_mfma_f32_16x16x32_bf16 v[88:91], v[226:229], v[202:205], v[88:91]
	v_mfma_f32_16x16x32_bf16 v[68:71], v[218:221], v[210:213], v[68:71]
	v_mfma_f32_16x16x32_bf16 v[72:75], v[226:229], v[210:213], v[72:75]
	v_mfma_f32_16x16x32_bf16 v[116:119], v[222:225], v[190:193], v[116:119]
	s_waitcnt lgkmcnt(0)
	v_mfma_f32_16x16x32_bf16 v[120:123], v[230:233], v[190:193], v[120:123]
	v_mfma_f32_16x16x32_bf16 v[100:103], v[222:225], v[198:201], v[100:103]
	v_mfma_f32_16x16x32_bf16 v[104:107], v[230:233], v[198:201], v[104:107]
	v_mfma_f32_16x16x32_bf16 v[84:87], v[222:225], v[206:209], v[84:87]
	v_mfma_f32_16x16x32_bf16 v[88:91], v[230:233], v[206:209], v[88:91]
	v_mfma_f32_16x16x32_bf16 v[68:71], v[222:225], v[214:217], v[68:71]
	v_mfma_f32_16x16x32_bf16 v[72:75], v[230:233], v[214:217], v[72:75]
	s_mov_b32 m0, s39
	v_lshl_add_u64 v[236:237], s[22:23], 0, v[134:135]
	s_barrier
	global_load_lds_dwordx4 v[236:237], off
	v_lshl_add_u64 v[238:239], s[22:23], 0, v[132:133]
	s_mov_b32 m0, s40
	s_nop 0
	global_load_lds_dwordx4 v[238:239], off
	ds_read_b128 v[174:177], v143 offset:16384
	ds_read_b128 v[190:193], v143 offset:17408
	ds_read_b128 v[194:197], v143 offset:18432
	ds_read_b128 v[198:201], v143 offset:19456
	ds_read_b128 v[202:205], v143 offset:20480
	ds_read_b128 v[206:209], v143 offset:21504
	ds_read_b128 v[210:213], v143 offset:22528
	ds_read_b128 v[214:217], v143 offset:23552
	s_barrier
	s_waitcnt lgkmcnt(7)
	v_mfma_f32_16x16x32_bf16 v[60:63], v[144:147], v[174:177], v[60:63]
	v_mfma_f32_16x16x32_bf16 v[64:67], v[166:169], v[174:177], v[64:67]
	s_waitcnt lgkmcnt(5)
	v_mfma_f32_16x16x32_bf16 v[44:47], v[144:147], v[194:197], v[44:47]
	v_mfma_f32_16x16x32_bf16 v[48:51], v[166:169], v[194:197], v[48:51]
	s_waitcnt lgkmcnt(3)
	v_mfma_f32_16x16x32_bf16 v[28:31], v[144:147], v[202:205], v[28:31]
	v_mfma_f32_16x16x32_bf16 v[32:35], v[166:169], v[202:205], v[32:35]
	s_waitcnt lgkmcnt(1)
	v_mfma_f32_16x16x32_bf16 v[12:15], v[144:147], v[210:213], v[12:15]
	v_mfma_f32_16x16x32_bf16 v[16:19], v[166:169], v[210:213], v[16:19]
	v_mfma_f32_16x16x32_bf16 v[60:63], v[162:165], v[190:193], v[60:63]
	v_mfma_f32_16x16x32_bf16 v[64:67], v[170:173], v[190:193], v[64:67]
	v_mfma_f32_16x16x32_bf16 v[44:47], v[162:165], v[198:201], v[44:47]
	v_mfma_f32_16x16x32_bf16 v[48:51], v[170:173], v[198:201], v[48:51]
	v_mfma_f32_16x16x32_bf16 v[28:31], v[162:165], v[206:209], v[28:31]
	v_mfma_f32_16x16x32_bf16 v[32:35], v[170:173], v[206:209], v[32:35]
	s_waitcnt lgkmcnt(0)
	v_mfma_f32_16x16x32_bf16 v[12:15], v[162:165], v[214:217], v[12:15]
	v_mfma_f32_16x16x32_bf16 v[16:19], v[170:173], v[214:217], v[16:19]
	s_barrier
; #define PG8_STAGE(bufoff, gbase, voff) do { _Pragma("unroll") for (int _i = 0; _i < 2; ++_i) \
;         __builtin_amdgcn_global_load_lds((const unsigned*)((const char*)(gbase) + (voff)[_i]), (LAS unsigned*)(lds + (bufoff) + ldsw + _i * 8192), 16, 0, 0); } while (0)
; #define PG8_LDA(dst, b, h) do { _Pragma("unroll") for (int m = 0; m < 4; ++m) _Pragma("unroll") for (int k = 0; k < 2; ++k) dst[m][k] = *(const LAS h8*)(lds + PG8_SA(b, h) + aoff + m * 2048 + k * 1024); } while (0)
; #define PG8_LDB(dst, b, h) do { _Pragma("unroll") for (int n = 0; n < 2; ++n) _Pragma("unroll") for (int k = 0; k < 2; ++k) dst[n][k] = *(const LAS h8*)(lds + PG8_SB(b, h) + boff + n * 2048 + k * 1024); } while (0)
; #define PG8_WAIT_V(n) asm volatile("s_waitcnt vmcnt(" #n ")" ::: "memory")
; #define PG8_WAIT_L(n) asm volatile("s_waitcnt lgkmcnt(" #n ")" ::: "memory")
; #define PG8_BAR __builtin_amdgcn_s_barrier()
; #define PG8_SCHED __builtin_amdgcn_sched_barrier(0)
; template <class Epi>
; __device__ __forceinline__ void gemm_phase(LAS unsigned char* lds, const Gemm g, const StaticOrder& S, const Epi& E, const int tid) {
;     ...
;             PG8_STAGE(PG8_SB(0, 1), b2 + hstepB, voffB);
;             PG8_WAIT_V(6); PG8_BAR; PG8_MMA(1, 1, At, B1); PG8_BAR;
;             PG8_LDB(B0, 1, 0); PG8_SCHED; PG8_LDA(At, 1, 0); PG8_STAGE(PG8_SA(0, 1), a2 + hstep, voffA);
;             PG8_WAIT_L(8); PG8_BAR; PG8_WAIT_L(0); PG8_MMA(0, 0, At, B0); PG8_BAR; PG8_SCHED;
;             PG8_LDB(B1, 1, 1); PG8_STAGE(PG8_SB(1, 0), b3, voffB);
;             PG8_BAR; PG8_WAIT_L(0); PG8_MMA(0, 1, At, B1); PG8_BAR;
	s_add_u32 s56, s18, 0x20000
	s_addc_u32 s57, s19, 0
	s_add_i32 s55, s58, s38
	s_mov_b32 m0, s55
	s_nop 0
	global_load_lds_dwordx4 v2, s[56:57]
	s_add_i32 m0, s55, 0x2000
	s_nop 0
	global_load_lds_dwordx4 v0, s[56:57]
	s_waitcnt vmcnt(6)
	s_barrier
	v_mfma_f32_16x16x32_bf16 v[52:55], v[218:221], v[174:177], v[52:55]
	v_mfma_f32_16x16x32_bf16 v[56:59], v[226:229], v[174:177], v[56:59]
	v_mfma_f32_16x16x32_bf16 v[36:39], v[218:221], v[194:197], v[36:39]
	v_mfma_f32_16x16x32_bf16 v[40:43], v[226:229], v[194:197], v[40:43]
	v_mfma_f32_16x16x32_bf16 v[20:23], v[218:221], v[202:205], v[20:23]
	v_mfma_f32_16x16x32_bf16 v[24:27], v[226:229], v[202:205], v[24:27]
	v_mfma_f32_16x16x32_bf16 v[8:11], v[218:221], v[210:213], v[8:11]
	v_mfma_f32_16x16x32_bf16 v[4:7], v[226:229], v[210:213], v[4:7]
	v_mfma_f32_16x16x32_bf16 v[52:55], v[222:225], v[190:193], v[52:55]
	v_mfma_f32_16x16x32_bf16 v[56:59], v[230:233], v[190:193], v[56:59]
	v_mfma_f32_16x16x32_bf16 v[36:39], v[222:225], v[198:201], v[36:39]
	v_mfma_f32_16x16x32_bf16 v[40:43], v[230:233], v[198:201], v[40:43]
	v_mfma_f32_16x16x32_bf16 v[20:23], v[222:225], v[206:209], v[20:23]
	v_mfma_f32_16x16x32_bf16 v[24:27], v[230:233], v[206:209], v[24:27]
	v_mfma_f32_16x16x32_bf16 v[8:11], v[222:225], v[214:217], v[8:11]
	v_mfma_f32_16x16x32_bf16 v[4:7], v[230:233], v[214:217], v[4:7]
	s_add_i32 s55, 0, 0x18000
	v_add_u32_e32 v157, s55, v140
	s_barrier
	s_add_u32 s22, s22, 0x80000
	s_addc_u32 s23, s23, 0
	s_mov_b32 m0, s41
	s_nop 0
	global_load_lds_dwordx4 v134, s[22:23]
	s_mov_b32 m0, s42
	s_nop 0
	global_load_lds_dwordx4 v132, s[22:23]
	ds_read_b128 v[144:147], v157
	ds_read_b128 v[162:165], v157 offset:1024
	ds_read_b128 v[166:169], v157 offset:2048
	ds_read_b128 v[170:173], v157 offset:3072
	ds_read_b128 v[174:177], v143 offset:32768
	ds_read_b128 v[190:193], v143 offset:33792
	ds_read_b128 v[194:197], v143 offset:34816
	ds_read_b128 v[198:201], v143 offset:35840
	ds_read_b128 v[202:205], v143 offset:36864
	ds_read_b128 v[206:209], v143 offset:37888
	ds_read_b128 v[210:213], v143 offset:38912
	ds_read_b128 v[214:217], v143 offset:39936
	s_waitcnt lgkmcnt(8)
	s_barrier
	s_waitcnt lgkmcnt(7)
	v_mfma_f32_16x16x32_bf16 v[124:127], v[144:147], v[174:177], v[124:127]
	v_mfma_f32_16x16x32_bf16 v[128:131], v[166:169], v[174:177], v[128:131]
	s_waitcnt lgkmcnt(5)
	v_mfma_f32_16x16x32_bf16 v[108:111], v[144:147], v[194:197], v[108:111]
	v_mfma_f32_16x16x32_bf16 v[112:115], v[166:169], v[194:197], v[112:115]
	s_waitcnt lgkmcnt(3)
	v_mfma_f32_16x16x32_bf16 v[92:95], v[144:147], v[202:205], v[92:95]
	v_mfma_f32_16x16x32_bf16 v[96:99], v[166:169], v[202:205], v[96:99]
	s_waitcnt lgkmcnt(1)
	v_mfma_f32_16x16x32_bf16 v[76:79], v[144:147], v[210:213], v[76:79]
	v_mfma_f32_16x16x32_bf16 v[80:83], v[166:169], v[210:213], v[80:83]
	v_mfma_f32_16x16x32_bf16 v[124:127], v[162:165], v[190:193], v[124:127]
	v_mfma_f32_16x16x32_bf16 v[128:131], v[170:173], v[190:193], v[128:131]
	v_mfma_f32_16x16x32_bf16 v[108:111], v[162:165], v[198:201], v[108:111]
	v_mfma_f32_16x16x32_bf16 v[112:115], v[170:173], v[198:201], v[112:115]
	v_mfma_f32_16x16x32_bf16 v[92:95], v[162:165], v[206:209], v[92:95]
	v_mfma_f32_16x16x32_bf16 v[96:99], v[170:173], v[206:209], v[96:99]
	s_waitcnt lgkmcnt(0)
	v_mfma_f32_16x16x32_bf16 v[76:79], v[162:165], v[214:217], v[76:79]
	v_mfma_f32_16x16x32_bf16 v[80:83], v[170:173], v[214:217], v[80:83]
	s_barrier
	s_add_i32 s22, 0, 0x1c000
	s_add_i32 s23, s55, s38
	v_add_u32_e32 v157, s22, v140
	v_lshl_add_u64 v[178:179], v[178:179], 0, s[30:31]
	s_mov_b32 m0, s23
	s_nop 0
	global_load_lds_dwordx4 v[178:179], off
	v_lshl_add_u64 v[178:179], v[234:235], 0, s[30:31]
	s_add_i32 m0, s23, 0x2000
	s_nop 0
	global_load_lds_dwordx4 v[178:179], off
	ds_read_b128 v[218:221], v157
	ds_read_b128 v[222:225], v157 offset:1024
	ds_read_b128 v[226:229], v157 offset:2048
	ds_read_b128 v[230:233], v157 offset:3072
	s_barrier
; #define PG8_STAGE(bufoff, gbase, voff) do { _Pragma("unroll") for (int _i = 0; _i < 2; ++_i) \
;         __builtin_amdgcn_global_load_lds((const unsigned*)((const char*)(gbase) + (voff)[_i]), (LAS unsigned*)(lds + (bufoff) + ldsw + _i * 8192), 16, 0, 0); } while (0)
; #define PG8_LDA(dst, b, h) do { _Pragma("unroll") for (int m = 0; m < 4; ++m) _Pragma("unroll") for (int k = 0; k < 2; ++k) dst[m][k] = *(const LAS h8*)(lds + PG8_SA(b, h) + aoff + m * 2048 + k * 1024); } while (0)
; #define PG8_WAIT_V(n) asm volatile("s_waitcnt vmcnt(" #n ")" ::: "memory")
; #define PG8_WAIT_L(n) asm volatile("s_waitcnt lgkmcnt(" #n ")" ::: "memory")
; #define PG8_BAR __builtin_amdgcn_s_barrier()
; #define PG8_SCHED __builtin_amdgcn_sched_barrier(0)
; template <class Epi>
; __device__ __forceinline__ void gemm_phase(LAS unsigned char* lds, const Gemm g, const StaticOrder& S, const Epi& E, const int tid) {
;     ...
;             PG8_BAR; PG8_WAIT_L(0); PG8_MMA(0, 1, At, B1); PG8_BAR;
;             PG8_LDA(At, 1, 1); PG8_STAGE(PG8_SA(1, 0), a3, voffA);
;             PG8_BAR; PG8_WAIT_L(0); PG8_MMA(1, 0, At, B0); PG8_BAR; PG8_SCHED;
;             PG8_STAGE(PG8_SB(1, 1), b3 + hstepB, voffB);
;             PG8_WAIT_V(6); PG8_BAR; PG8_MMA(1, 1, At, B1); PG8_BAR;
	s_waitcnt lgkmcnt(3)
	v_mfma_f32_16x16x32_bf16 v[116:119], v[218:221], v[174:177], v[116:119]
	s_waitcnt lgkmcnt(1)
	v_mfma_f32_16x16x32_bf16 v[120:123], v[226:229], v[174:177], v[120:123]
	v_mfma_f32_16x16x32_bf16 v[100:103], v[218:221], v[194:197], v[100:103]
	v_mfma_f32_16x16x32_bf16 v[104:107], v[226:229], v[194:197], v[104:107]
	v_mfma_f32_16x16x32_bf16 v[84:87], v[218:221], v[202:205], v[84:87]
	v_mfma_f32_16x16x32_bf16 v[88:91], v[226:229], v[202:205], v[88:91]
	v_mfma_f32_16x16x32_bf16 v[68:71], v[218:221], v[210:213], v[68:71]
	v_mfma_f32_16x16x32_bf16 v[72:75], v[226:229], v[210:213], v[72:75]
	v_mfma_f32_16x16x32_bf16 v[116:119], v[222:225], v[190:193], v[116:119]
	s_waitcnt lgkmcnt(0)
	v_mfma_f32_16x16x32_bf16 v[120:123], v[230:233], v[190:193], v[120:123]
	v_mfma_f32_16x16x32_bf16 v[100:103], v[222:225], v[198:201], v[100:103]
	v_mfma_f32_16x16x32_bf16 v[104:107], v[230:233], v[198:201], v[104:107]
	v_mfma_f32_16x16x32_bf16 v[84:87], v[222:225], v[206:209], v[84:87]
	v_mfma_f32_16x16x32_bf16 v[88:91], v[230:233], v[206:209], v[88:91]
	v_mfma_f32_16x16x32_bf16 v[68:71], v[222:225], v[214:217], v[68:71]
	v_mfma_f32_16x16x32_bf16 v[72:75], v[230:233], v[214:217], v[72:75]
	s_mov_b32 m0, s43
	v_lshl_add_u64 v[178:179], v[236:237], 0, s[30:31]
	s_barrier
	global_load_lds_dwordx4 v[178:179], off
	v_lshl_add_u64 v[178:179], v[238:239], 0, s[30:31]
	s_mov_b32 m0, s46
	s_nop 0
	global_load_lds_dwordx4 v[178:179], off
	ds_read_b128 v[174:177], v143 offset:49152
	ds_read_b128 v[190:193], v143 offset:50176
	ds_read_b128 v[194:197], v143 offset:51200
	ds_read_b128 v[198:201], v143 offset:52224
	ds_read_b128 v[202:205], v143 offset:53248
	ds_read_b128 v[206:209], v143 offset:54272
	ds_read_b128 v[210:213], v143 offset:55296
	ds_read_b128 v[214:217], v143 offset:56320
	s_barrier
	s_waitcnt lgkmcnt(7)
	v_mfma_f32_16x16x32_bf16 v[60:63], v[144:147], v[174:177], v[60:63]
	v_mfma_f32_16x16x32_bf16 v[64:67], v[166:169], v[174:177], v[64:67]
	s_waitcnt lgkmcnt(5)
	v_mfma_f32_16x16x32_bf16 v[44:47], v[144:147], v[194:197], v[44:47]
	v_mfma_f32_16x16x32_bf16 v[48:51], v[166:169], v[194:197], v[48:51]
	s_waitcnt lgkmcnt(3)
	v_mfma_f32_16x16x32_bf16 v[28:31], v[144:147], v[202:205], v[28:31]
	v_mfma_f32_16x16x32_bf16 v[32:35], v[166:169], v[202:205], v[32:35]
	s_waitcnt lgkmcnt(1)
	v_mfma_f32_16x16x32_bf16 v[12:15], v[144:147], v[210:213], v[12:15]
	v_mfma_f32_16x16x32_bf16 v[16:19], v[166:169], v[210:213], v[16:19]
	v_mfma_f32_16x16x32_bf16 v[60:63], v[162:165], v[190:193], v[60:63]
	v_mfma_f32_16x16x32_bf16 v[64:67], v[170:173], v[190:193], v[64:67]
	v_mfma_f32_16x16x32_bf16 v[44:47], v[162:165], v[198:201], v[44:47]
	v_mfma_f32_16x16x32_bf16 v[48:51], v[170:173], v[198:201], v[48:51]
	v_mfma_f32_16x16x32_bf16 v[28:31], v[162:165], v[206:209], v[28:31]
	v_mfma_f32_16x16x32_bf16 v[32:35], v[170:173], v[206:209], v[32:35]
	s_waitcnt lgkmcnt(0)
	v_mfma_f32_16x16x32_bf16 v[12:15], v[162:165], v[214:217], v[12:15]
	v_mfma_f32_16x16x32_bf16 v[16:19], v[170:173], v[214:217], v[16:19]
	s_barrier
	s_add_u32 s18, s18, 0x20080
	s_addc_u32 s19, s19, 0
	s_add_i32 s22, s22, s38
	s_mov_b32 m0, s22
	s_nop 0
	global_load_lds_dwordx4 v2, s[18:19]
	v_lshl_add_u64 v[144:145], s[18:19], 0, v[0:1]
	s_add_i32 m0, s22, 0x2000
	s_nop 0
	global_load_lds_dwordx4 v[144:145], off
	s_waitcnt vmcnt(6)
	s_barrier
	v_mfma_f32_16x16x32_bf16 v[52:55], v[218:221], v[174:177], v[52:55]
	v_mfma_f32_16x16x32_bf16 v[56:59], v[226:229], v[174:177], v[56:59]
	v_mfma_f32_16x16x32_bf16 v[36:39], v[218:221], v[194:197], v[36:39]
	v_mfma_f32_16x16x32_bf16 v[40:43], v[226:229], v[194:197], v[40:43]
	v_mfma_f32_16x16x32_bf16 v[20:23], v[218:221], v[202:205], v[20:23]
	v_mfma_f32_16x16x32_bf16 v[24:27], v[226:229], v[202:205], v[24:27]
	v_mfma_f32_16x16x32_bf16 v[8:11], v[218:221], v[210:213], v[8:11]
	v_mfma_f32_16x16x32_bf16 v[4:7], v[226:229], v[210:213], v[4:7]
	v_mfma_f32_16x16x32_bf16 v[52:55], v[222:225], v[190:193], v[52:55]
	v_mfma_f32_16x16x32_bf16 v[56:59], v[230:233], v[190:193], v[56:59]
	v_mfma_f32_16x16x32_bf16 v[36:39], v[222:225], v[198:201], v[36:39]
	v_mfma_f32_16x16x32_bf16 v[40:43], v[230:233], v[198:201], v[40:43]
	v_mfma_f32_16x16x32_bf16 v[20:23], v[222:225], v[206:209], v[20:23]
	v_mfma_f32_16x16x32_bf16 v[24:27], v[230:233], v[206:209], v[24:27]
	v_mfma_f32_16x16x32_bf16 v[8:11], v[222:225], v[214:217], v[8:11]
	v_mfma_f32_16x16x32_bf16 v[4:7], v[230:233], v[214:217], v[4:7]
	s_add_i32 s54, s54, 2
	s_add_u32 s14, s14, 0x100
	s_addc_u32 s15, s15, 0
	s_add_u32 s52, s52, 0x100
	s_addc_u32 s53, s53, 0
	s_cmp_gt_u32 s54, 29
	s_barrier
	s_cbranch_scc0 .LBB0_332
	s_cmp_lt_u32 s48, 24
	s_cbranch_scc1 .Lepi_stream
	s_cmp_lt_u32 s48, 44
	s_cbranch_scc1 .Lepi_cached
